# prompt indexer score loop: head loop unrolled 8x (no weight-select chain, no canonicalising max, scalar fmac), first key-block fragments loaded before the staging barrier, counted waits no longer wait
# speedup vs baseline: 1.0090x; 1.0090x over previous
.LBB0_706:
	s_or_b64 exec, exec, s[0:1]
	v_readlane_b32 s0, v252, 29
	s_waitcnt lgkmcnt(0)
	s_barrier
	v_mov_b32_e32 v1, s0
	ds_read_b32 v1, v1
	s_mov_b64 s[0:1], -1
	s_waitcnt lgkmcnt(0)
	v_cmp_lt_i32_e32 vcc, s87, v1
	v_readfirstlane_b32 s2, v1
	s_cbranch_vccnz .LBB0_701
	s_ashr_i32 s0, s2, 2
	s_and_b32 s4, s2, 3
	s_sub_i32 s5, 63, s0
	s_lshl_b32 s2, s4, 11
	s_lshl_b32 s89, s5, 5
	s_add_i32 s13, s89, s2
	v_or_b32_e32 v74, s13, v152
	v_lshlrev_b64 v[2:3], 10, v[74:75]
	v_or_b32_e32 v74, s13, v150
	v_readlane_b32 s0, v252, 17
	v_lshlrev_b64 v[18:19], 5, v[74:75]
	v_readlane_b32 s1, v252, 18
	v_lshl_add_u64 v[14:15], v[76:77], 0, v[2:3]
	global_load_dwordx4 v[2:5], v[14:15], off offset:48
	global_load_dwordx4 v[6:9], v[14:15], off offset:32
	global_load_dwordx4 v[10:13], v[14:15], off offset:16
	s_nop 0
	global_load_dwordx4 v[14:17], v[14:15], off
	v_lshl_add_u64 v[18:19], s[0:1], 0, v[18:19]
	global_load_dwordx4 v[184:187], v[18:19], off
	global_load_dwordx4 v[188:191], v[18:19], off offset:16
	v_add_u32_e32 v192, s2, v153
	v_mov_b32_e32 v193, 0
	v_lshlrev_b64 v[192:193], 7, v[192:193]
	v_lshl_add_u64 v[192:193], v[78:79], 0, v[192:193]
	global_load_dwordx4 v[26:29], v[192:193], off
	global_load_dwordx4 v[30:33], v[192:193], off offset:32
	global_load_dwordx4 v[34:37], v[192:193], off offset:64
	global_load_dwordx4 v[38:41], v[192:193], off offset:96
	s_cmp_le_i32 s88, s5
	s_cselect_b64 s[0:1], -1, 0
	s_waitcnt vmcnt(6)
	ds_write_b128 v160, v[14:17]
	ds_write_b128 v160, v[10:13] offset:16
	ds_write_b128 v160, v[6:9] offset:32
	ds_write_b128 v160, v[2:5] offset:48
	s_waitcnt vmcnt(4)
	v_mul_f32_e32 v18, 0x3d3504f3, v184
	v_mul_f32_e32 v20, 0x3d3504f3, v188
	v_mul_f32_e32 v1, 0x3d3504f3, v185
	v_mul_f32_e32 v19, 0x3d3504f3, v189
	v_mul_f32_e32 v22, 0x3d3504f3, v186
	v_mul_f32_e32 v24, 0x3d3504f3, v190
	v_mul_f32_e32 v21, 0x3d3504f3, v187
	v_mul_f32_e32 v23, 0x3d3504f3, v191
	s_waitcnt lgkmcnt(0)
	s_barrier
.LBB0_710:
	v_readlane_b32 s6, v252, 21
	v_readlane_b32 s7, v252, 22
	s_andn2_b64 vcc, exec, s[6:7]
	s_cbranch_vccnz .LBB0_718
	s_andn2_b64 vcc, exec, s[0:1]
	s_cbranch_vccnz .LBB0_718
	v_lshlrev_b64 v[2:3], 13, v[74:75]
	v_or_b32_e32 v25, s2, v150
	v_lshl_add_u64 v[148:149], v[80:81], 0, v[2:3]
	s_mov_b32 s6, s88
	s_waitcnt vmcnt(0)
.LBB0_713:
	s_add_i32 s7, s6, 8
	s_cmp_gt_i32 s7, s5
	s_cselect_b64 s[0:1], -1, 0
	s_cbranch_scc1 .Lidxp_nopf
	v_lshl_add_u32 v2, s7, 5, v25
	v_ashrrev_i32_e32 v3, 31, v2
	v_lshlrev_b64 v[2:3], 7, v[2:3]
	v_lshl_add_u64 v[2:3], v[78:79], 0, v[2:3]
	global_load_dwordx4 v[54:57], v[2:3], off
	global_load_dwordx4 v[50:53], v[2:3], off offset:32
	global_load_dwordx4 v[46:49], v[2:3], off offset:64
	global_load_dwordx4 v[42:45], v[2:3], off offset:96
.Lidxp_nopf:
	ds_read_b128 v[194:197], v154
	ds_read_b128 v[166:169], v154 offset:32
	ds_read_b128 v[170:173], v154 offset:64
	ds_read_b128 v[174:177], v154 offset:96
	s_waitcnt lgkmcnt(3)
	v_mfma_f32_32x32x16_bf16 v[2:17], v[26:29], v[194:197], 0
	s_waitcnt lgkmcnt(2)
	v_mfma_f32_32x32x16_bf16 v[2:17], v[30:33], v[166:169], v[2:17]
	s_waitcnt lgkmcnt(1)
	v_mfma_f32_32x32x16_bf16 v[2:17], v[34:37], v[170:173], v[2:17]
	s_waitcnt lgkmcnt(0)
	v_mfma_f32_32x32x16_bf16 v[2:17], v[38:41], v[174:177], v[2:17]
	ds_read_b128 v[194:197], v154 offset:128
	ds_read_b128 v[166:169], v154 offset:160
	ds_read_b128 v[170:173], v154 offset:192
	ds_read_b128 v[174:177], v154 offset:224
	s_nop 7
	v_max_f32_e32 v2, 0, v2
	v_max_f32_e32 v3, 0, v3
	v_max_f32_e32 v4, 0, v4
	v_max_f32_e32 v5, 0, v5
	v_max_f32_e32 v6, 0, v6
	v_max_f32_e32 v7, 0, v7
	v_max_f32_e32 v8, 0, v8
	v_max_f32_e32 v9, 0, v9
	v_max_f32_e32 v10, 0, v10
	v_max_f32_e32 v11, 0, v11
	v_max_f32_e32 v12, 0, v12
	v_max_f32_e32 v13, 0, v13
	v_max_f32_e32 v14, 0, v14
	v_max_f32_e32 v15, 0, v15
	v_max_f32_e32 v16, 0, v16
	v_max_f32_e32 v17, 0, v17
	v_mul_f32_e32 v70, v18, v2
	v_mul_f32_e32 v71, v18, v3
	v_mul_f32_e32 v72, v18, v4
	v_mul_f32_e32 v73, v18, v5
	v_mul_f32_e32 v66, v18, v6
	v_mul_f32_e32 v67, v18, v7
	v_mul_f32_e32 v68, v18, v8
	v_mul_f32_e32 v69, v18, v9
	v_mul_f32_e32 v62, v18, v10
	v_mul_f32_e32 v63, v18, v11
	v_mul_f32_e32 v64, v18, v12
	v_mul_f32_e32 v65, v18, v13
	v_mul_f32_e32 v58, v18, v14
	v_mul_f32_e32 v59, v18, v15
	v_mul_f32_e32 v60, v18, v16
	v_mul_f32_e32 v61, v18, v17
	s_waitcnt lgkmcnt(3)
	v_mfma_f32_32x32x16_bf16 v[2:17], v[26:29], v[194:197], 0
	s_waitcnt lgkmcnt(2)
	v_mfma_f32_32x32x16_bf16 v[2:17], v[30:33], v[166:169], v[2:17]
	s_waitcnt lgkmcnt(1)
	v_mfma_f32_32x32x16_bf16 v[2:17], v[34:37], v[170:173], v[2:17]
	s_waitcnt lgkmcnt(0)
	v_mfma_f32_32x32x16_bf16 v[2:17], v[38:41], v[174:177], v[2:17]
	ds_read_b128 v[194:197], v154 offset:256
	ds_read_b128 v[166:169], v154 offset:288
	ds_read_b128 v[170:173], v154 offset:320
	ds_read_b128 v[174:177], v154 offset:352
	s_nop 7
	v_max_f32_e32 v2, 0, v2
	v_max_f32_e32 v3, 0, v3
	v_max_f32_e32 v4, 0, v4
	v_max_f32_e32 v5, 0, v5
	v_max_f32_e32 v6, 0, v6
	v_max_f32_e32 v7, 0, v7
	v_max_f32_e32 v8, 0, v8
	v_max_f32_e32 v9, 0, v9
	v_max_f32_e32 v10, 0, v10
	v_max_f32_e32 v11, 0, v11
	v_max_f32_e32 v12, 0, v12
	v_max_f32_e32 v13, 0, v13
	v_max_f32_e32 v14, 0, v14
	v_max_f32_e32 v15, 0, v15
	v_max_f32_e32 v16, 0, v16
	v_max_f32_e32 v17, 0, v17
	v_fmac_f32_e32 v70, v1, v2
	v_fmac_f32_e32 v71, v1, v3
	v_fmac_f32_e32 v72, v1, v4
	v_fmac_f32_e32 v73, v1, v5
	v_fmac_f32_e32 v66, v1, v6
	v_fmac_f32_e32 v67, v1, v7
	v_fmac_f32_e32 v68, v1, v8
	v_fmac_f32_e32 v69, v1, v9
	v_fmac_f32_e32 v62, v1, v10
	v_fmac_f32_e32 v63, v1, v11
	v_fmac_f32_e32 v64, v1, v12
	v_fmac_f32_e32 v65, v1, v13
	v_fmac_f32_e32 v58, v1, v14
	v_fmac_f32_e32 v59, v1, v15
	v_fmac_f32_e32 v60, v1, v16
	v_fmac_f32_e32 v61, v1, v17
	s_waitcnt lgkmcnt(3)
	v_mfma_f32_32x32x16_bf16 v[2:17], v[26:29], v[194:197], 0
	s_waitcnt lgkmcnt(2)
	v_mfma_f32_32x32x16_bf16 v[2:17], v[30:33], v[166:169], v[2:17]
	s_waitcnt lgkmcnt(1)
	v_mfma_f32_32x32x16_bf16 v[2:17], v[34:37], v[170:173], v[2:17]
	s_waitcnt lgkmcnt(0)
	v_mfma_f32_32x32x16_bf16 v[2:17], v[38:41], v[174:177], v[2:17]
	ds_read_b128 v[194:197], v154 offset:384
	ds_read_b128 v[166:169], v154 offset:416
	ds_read_b128 v[170:173], v154 offset:448
	ds_read_b128 v[174:177], v154 offset:480
	s_nop 7
	v_max_f32_e32 v2, 0, v2
	v_max_f32_e32 v3, 0, v3
	v_max_f32_e32 v4, 0, v4
	v_max_f32_e32 v5, 0, v5
	v_max_f32_e32 v6, 0, v6
	v_max_f32_e32 v7, 0, v7
	v_max_f32_e32 v8, 0, v8
	v_max_f32_e32 v9, 0, v9
	v_max_f32_e32 v10, 0, v10
	v_max_f32_e32 v11, 0, v11
	v_max_f32_e32 v12, 0, v12
	v_max_f32_e32 v13, 0, v13
	v_max_f32_e32 v14, 0, v14
	v_max_f32_e32 v15, 0, v15
	v_max_f32_e32 v16, 0, v16
	v_max_f32_e32 v17, 0, v17
	v_fmac_f32_e32 v70, v22, v2
	v_fmac_f32_e32 v71, v22, v3
	v_fmac_f32_e32 v72, v22, v4
	v_fmac_f32_e32 v73, v22, v5
	v_fmac_f32_e32 v66, v22, v6
	v_fmac_f32_e32 v67, v22, v7
	v_fmac_f32_e32 v68, v22, v8
	v_fmac_f32_e32 v69, v22, v9
	v_fmac_f32_e32 v62, v22, v10
	v_fmac_f32_e32 v63, v22, v11
	v_fmac_f32_e32 v64, v22, v12
	v_fmac_f32_e32 v65, v22, v13
	v_fmac_f32_e32 v58, v22, v14
	v_fmac_f32_e32 v59, v22, v15
	v_fmac_f32_e32 v60, v22, v16
	v_fmac_f32_e32 v61, v22, v17
	s_waitcnt lgkmcnt(3)
	v_mfma_f32_32x32x16_bf16 v[2:17], v[26:29], v[194:197], 0
	s_waitcnt lgkmcnt(2)
	v_mfma_f32_32x32x16_bf16 v[2:17], v[30:33], v[166:169], v[2:17]
	s_waitcnt lgkmcnt(1)
	v_mfma_f32_32x32x16_bf16 v[2:17], v[34:37], v[170:173], v[2:17]
	s_waitcnt lgkmcnt(0)
	v_mfma_f32_32x32x16_bf16 v[2:17], v[38:41], v[174:177], v[2:17]
	ds_read_b128 v[194:197], v154 offset:512
	ds_read_b128 v[166:169], v154 offset:544
	ds_read_b128 v[170:173], v154 offset:576
	ds_read_b128 v[174:177], v154 offset:608
	s_nop 7
	v_max_f32_e32 v2, 0, v2
	v_max_f32_e32 v3, 0, v3
	v_max_f32_e32 v4, 0, v4
	v_max_f32_e32 v5, 0, v5
	v_max_f32_e32 v6, 0, v6
	v_max_f32_e32 v7, 0, v7
	v_max_f32_e32 v8, 0, v8
	v_max_f32_e32 v9, 0, v9
	v_max_f32_e32 v10, 0, v10
	v_max_f32_e32 v11, 0, v11
	v_max_f32_e32 v12, 0, v12
	v_max_f32_e32 v13, 0, v13
	v_max_f32_e32 v14, 0, v14
	v_max_f32_e32 v15, 0, v15
	v_max_f32_e32 v16, 0, v16
	v_max_f32_e32 v17, 0, v17
	v_fmac_f32_e32 v70, v21, v2
	v_fmac_f32_e32 v71, v21, v3
	v_fmac_f32_e32 v72, v21, v4
	v_fmac_f32_e32 v73, v21, v5
	v_fmac_f32_e32 v66, v21, v6
	v_fmac_f32_e32 v67, v21, v7
	v_fmac_f32_e32 v68, v21, v8
	v_fmac_f32_e32 v69, v21, v9
	v_fmac_f32_e32 v62, v21, v10
	v_fmac_f32_e32 v63, v21, v11
	v_fmac_f32_e32 v64, v21, v12
	v_fmac_f32_e32 v65, v21, v13
	v_fmac_f32_e32 v58, v21, v14
	v_fmac_f32_e32 v59, v21, v15
	v_fmac_f32_e32 v60, v21, v16
	v_fmac_f32_e32 v61, v21, v17
	s_waitcnt lgkmcnt(3)
	v_mfma_f32_32x32x16_bf16 v[2:17], v[26:29], v[194:197], 0
	s_waitcnt lgkmcnt(2)
	v_mfma_f32_32x32x16_bf16 v[2:17], v[30:33], v[166:169], v[2:17]
	s_waitcnt lgkmcnt(1)
	v_mfma_f32_32x32x16_bf16 v[2:17], v[34:37], v[170:173], v[2:17]
	s_waitcnt lgkmcnt(0)
	v_mfma_f32_32x32x16_bf16 v[2:17], v[38:41], v[174:177], v[2:17]
	ds_read_b128 v[194:197], v154 offset:640
	ds_read_b128 v[166:169], v154 offset:672
	ds_read_b128 v[170:173], v154 offset:704
	ds_read_b128 v[174:177], v154 offset:736
	s_nop 7
	v_max_f32_e32 v2, 0, v2
	v_max_f32_e32 v3, 0, v3
	v_max_f32_e32 v4, 0, v4
	v_max_f32_e32 v5, 0, v5
	v_max_f32_e32 v6, 0, v6
	v_max_f32_e32 v7, 0, v7
	v_max_f32_e32 v8, 0, v8
	v_max_f32_e32 v9, 0, v9
	v_max_f32_e32 v10, 0, v10
	v_max_f32_e32 v11, 0, v11
	v_max_f32_e32 v12, 0, v12
	v_max_f32_e32 v13, 0, v13
	v_max_f32_e32 v14, 0, v14
	v_max_f32_e32 v15, 0, v15
	v_max_f32_e32 v16, 0, v16
	v_max_f32_e32 v17, 0, v17
	v_fmac_f32_e32 v70, v20, v2
	v_fmac_f32_e32 v71, v20, v3
	v_fmac_f32_e32 v72, v20, v4
	v_fmac_f32_e32 v73, v20, v5
	v_fmac_f32_e32 v66, v20, v6
	v_fmac_f32_e32 v67, v20, v7
	v_fmac_f32_e32 v68, v20, v8
	v_fmac_f32_e32 v69, v20, v9
	v_fmac_f32_e32 v62, v20, v10
	v_fmac_f32_e32 v63, v20, v11
	v_fmac_f32_e32 v64, v20, v12
	v_fmac_f32_e32 v65, v20, v13
	v_fmac_f32_e32 v58, v20, v14
	v_fmac_f32_e32 v59, v20, v15
	v_fmac_f32_e32 v60, v20, v16
	v_fmac_f32_e32 v61, v20, v17
	s_waitcnt lgkmcnt(3)
	v_mfma_f32_32x32x16_bf16 v[2:17], v[26:29], v[194:197], 0
	s_waitcnt lgkmcnt(2)
	v_mfma_f32_32x32x16_bf16 v[2:17], v[30:33], v[166:169], v[2:17]
	s_waitcnt lgkmcnt(1)
	v_mfma_f32_32x32x16_bf16 v[2:17], v[34:37], v[170:173], v[2:17]
	s_waitcnt lgkmcnt(0)
	v_mfma_f32_32x32x16_bf16 v[2:17], v[38:41], v[174:177], v[2:17]
	ds_read_b128 v[194:197], v154 offset:768
	ds_read_b128 v[166:169], v154 offset:800
	ds_read_b128 v[170:173], v154 offset:832
	ds_read_b128 v[174:177], v154 offset:864
	s_nop 7
	v_max_f32_e32 v2, 0, v2
	v_max_f32_e32 v3, 0, v3
	v_max_f32_e32 v4, 0, v4
	v_max_f32_e32 v5, 0, v5
	v_max_f32_e32 v6, 0, v6
	v_max_f32_e32 v7, 0, v7
	v_max_f32_e32 v8, 0, v8
	v_max_f32_e32 v9, 0, v9
	v_max_f32_e32 v10, 0, v10
	v_max_f32_e32 v11, 0, v11
	v_max_f32_e32 v12, 0, v12
	v_max_f32_e32 v13, 0, v13
	v_max_f32_e32 v14, 0, v14
	v_max_f32_e32 v15, 0, v15
	v_max_f32_e32 v16, 0, v16
	v_max_f32_e32 v17, 0, v17
	v_fmac_f32_e32 v70, v19, v2
	v_fmac_f32_e32 v71, v19, v3
	v_fmac_f32_e32 v72, v19, v4
	v_fmac_f32_e32 v73, v19, v5
	v_fmac_f32_e32 v66, v19, v6
	v_fmac_f32_e32 v67, v19, v7
	v_fmac_f32_e32 v68, v19, v8
	v_fmac_f32_e32 v69, v19, v9
	v_fmac_f32_e32 v62, v19, v10
	v_fmac_f32_e32 v63, v19, v11
	v_fmac_f32_e32 v64, v19, v12
	v_fmac_f32_e32 v65, v19, v13
	v_fmac_f32_e32 v58, v19, v14
	v_fmac_f32_e32 v59, v19, v15
	v_fmac_f32_e32 v60, v19, v16
	v_fmac_f32_e32 v61, v19, v17
	s_waitcnt lgkmcnt(3)
	v_mfma_f32_32x32x16_bf16 v[2:17], v[26:29], v[194:197], 0
	s_waitcnt lgkmcnt(2)
	v_mfma_f32_32x32x16_bf16 v[2:17], v[30:33], v[166:169], v[2:17]
	s_waitcnt lgkmcnt(1)
	v_mfma_f32_32x32x16_bf16 v[2:17], v[34:37], v[170:173], v[2:17]
	s_waitcnt lgkmcnt(0)
	v_mfma_f32_32x32x16_bf16 v[2:17], v[38:41], v[174:177], v[2:17]
	ds_read_b128 v[194:197], v154 offset:896
	ds_read_b128 v[166:169], v154 offset:928
	ds_read_b128 v[170:173], v154 offset:960
	ds_read_b128 v[174:177], v154 offset:992
	s_nop 7
	v_max_f32_e32 v2, 0, v2
	v_max_f32_e32 v3, 0, v3
	v_max_f32_e32 v4, 0, v4
	v_max_f32_e32 v5, 0, v5
	v_max_f32_e32 v6, 0, v6
	v_max_f32_e32 v7, 0, v7
	v_max_f32_e32 v8, 0, v8
	v_max_f32_e32 v9, 0, v9
	v_max_f32_e32 v10, 0, v10
	v_max_f32_e32 v11, 0, v11
	v_max_f32_e32 v12, 0, v12
	v_max_f32_e32 v13, 0, v13
	v_max_f32_e32 v14, 0, v14
	v_max_f32_e32 v15, 0, v15
	v_max_f32_e32 v16, 0, v16
	v_max_f32_e32 v17, 0, v17
	v_fmac_f32_e32 v70, v24, v2
	v_fmac_f32_e32 v71, v24, v3
	v_fmac_f32_e32 v72, v24, v4
	v_fmac_f32_e32 v73, v24, v5
	v_fmac_f32_e32 v66, v24, v6
	v_fmac_f32_e32 v67, v24, v7
	v_fmac_f32_e32 v68, v24, v8
	v_fmac_f32_e32 v69, v24, v9
	v_fmac_f32_e32 v62, v24, v10
	v_fmac_f32_e32 v63, v24, v11
	v_fmac_f32_e32 v64, v24, v12
	v_fmac_f32_e32 v65, v24, v13
	v_fmac_f32_e32 v58, v24, v14
	v_fmac_f32_e32 v59, v24, v15
	v_fmac_f32_e32 v60, v24, v16
	v_fmac_f32_e32 v61, v24, v17
	s_waitcnt lgkmcnt(3)
	v_mfma_f32_32x32x16_bf16 v[2:17], v[26:29], v[194:197], 0
	s_waitcnt lgkmcnt(2)
	v_mfma_f32_32x32x16_bf16 v[2:17], v[30:33], v[166:169], v[2:17]
	s_waitcnt lgkmcnt(1)
	v_mfma_f32_32x32x16_bf16 v[2:17], v[34:37], v[170:173], v[2:17]
	s_waitcnt lgkmcnt(0)
	v_mfma_f32_32x32x16_bf16 v[2:17], v[38:41], v[174:177], v[2:17]
	s_nop 7
	s_nop 3
	v_max_f32_e32 v2, 0, v2
	v_max_f32_e32 v3, 0, v3
	v_max_f32_e32 v4, 0, v4
	v_max_f32_e32 v5, 0, v5
	v_max_f32_e32 v6, 0, v6
	v_max_f32_e32 v7, 0, v7
	v_max_f32_e32 v8, 0, v8
	v_max_f32_e32 v9, 0, v9
	v_max_f32_e32 v10, 0, v10
	v_max_f32_e32 v11, 0, v11
	v_max_f32_e32 v12, 0, v12
	v_max_f32_e32 v13, 0, v13
	v_max_f32_e32 v14, 0, v14
	v_max_f32_e32 v15, 0, v15
	v_max_f32_e32 v16, 0, v16
	v_max_f32_e32 v17, 0, v17
	v_fmac_f32_e32 v70, v23, v2
	v_fmac_f32_e32 v71, v23, v3
	v_fmac_f32_e32 v72, v23, v4
	v_fmac_f32_e32 v73, v23, v5
	v_fmac_f32_e32 v66, v23, v6
	v_fmac_f32_e32 v67, v23, v7
	v_fmac_f32_e32 v68, v23, v8
	v_fmac_f32_e32 v69, v23, v9
	v_fmac_f32_e32 v62, v23, v10
	v_fmac_f32_e32 v63, v23, v11
	v_fmac_f32_e32 v64, v23, v12
	v_fmac_f32_e32 v65, v23, v13
	v_fmac_f32_e32 v58, v23, v14
	v_fmac_f32_e32 v59, v23, v15
	v_fmac_f32_e32 v60, v23, v16
	v_fmac_f32_e32 v61, v23, v17
	s_lshl_b32 s46, s6, 5
	v_lshl_add_u64 v[2:3], s[46:47], 2, v[148:149]
	s_waitcnt vmcnt(0)
	s_mov_b32 s6, s7
	v_mov_b32_e32 v26, v54
	v_mov_b32_e32 v27, v55
	v_mov_b32_e32 v28, v56
	v_mov_b32_e32 v29, v57
	v_mov_b32_e32 v30, v50
	v_mov_b32_e32 v31, v51
	v_mov_b32_e32 v32, v52
	v_mov_b32_e32 v33, v53
	v_mov_b32_e32 v34, v46
	v_mov_b32_e32 v35, v47
	v_mov_b32_e32 v36, v48
	v_mov_b32_e32 v37, v49
	v_mov_b32_e32 v38, v42
	v_mov_b32_e32 v39, v43
	v_mov_b32_e32 v40, v44
	v_mov_b32_e32 v41, v45
	global_store_dwordx4 v[2:3], v[70:73], off
	global_store_dwordx4 v[2:3], v[66:69], off offset:32
	global_store_dwordx4 v[2:3], v[62:65], off offset:64
	global_store_dwordx4 v[2:3], v[58:61], off offset:96
	s_and_b64 vcc, exec, s[0:1]
	s_cbranch_vccz .LBB0_713
